# phase 9: grid sync after ptanh split into arrive / wait with the W1Z and W1OUT transposes executed in between (instead of after rwkv2)
# speedup vs baseline: 1.0114x; 1.0114x over previous
; __global__ void __launch_bounds__(512, 2) mega(Params p) {
;     ...
;     if (IN(9)) {
;     ...
;         ptanh_phase(p);
;         grid.sync();
;         { const unsigned long long tw_ = rwkv2_phase(p, smem); if (PROBE_ROLE >= 0) tp1 += tw_; }
;     ...
;         rwkv_phase(p, smem);
;     ...
;         tconv(smem, p.in[24], 16384, 12288, 4096, 2048, (u16*)(ws + OFF_W1Z), 2048); if ((REP_MASK >> 4) & 1) { tconv(smem, p.in[24], 16384, 12288, 4096, 2048, (u16*)(ws + OFF_W1Z), 2048); }
;         tconv(smem, p.in[39], 2048, 0, 2048, 4096, (u16*)(ws + OFF_W1OUT), 4096); if ((REP_MASK >> 4) & 1) { tconv(smem, p.in[39], 2048, 0, 2048, 4096, (u16*)(ws + OFF_W1OUT), 4096); }
.LBB0_832:
	s_or_b64 exec, exec, s[0:1]
	v_lshrrev_b32_e32 v1, 20, v0
	v_lshrrev_b32_e32 v2, 10, v0
	v_or_b32_e32 v1, v2, v1
	s_movk_i32 s0, 0x3ff
	v_and_or_b32 v1, v1, s0, v103
	v_cmp_eq_u32_e32 vcc, 0, v1
	s_waitcnt lgkmcnt(0)
	s_barrier
	s_and_saveexec_b64 s[0:1], vcc
	s_cbranch_execz SPLIT9_tconv
	s_load_dwordx2 s[2:3], s[68:69], 0x58
	s_getreg_b32 s101, hwreg(HW_REG_XCC_ID)
	s_and_b32 s101, s101, 7
	s_lshr_b32 s98, s101, 1
	s_lshl_b32 s98, s98, 2
	s_and_b32 s99, s101, 1
	s_lshl_b32 s99, s99, 4
	v_mov_b32_e32 v3, s98
	v_mov_b32_e32 v1, 1
	v_lshlrev_b32_e32 v1, s99, v1
	s_waitcnt vmcnt(0) lgkmcnt(0)
	global_atomic_add v2, v3, v1, s[2:3] offset:16 sc0
	s_load_dword s101, s[2:3], 0x28
	s_waitcnt vmcnt(0)
	v_lshrrev_b32_e32 v2, s99, v2
	v_and_b32_e32 v2, 0xffff, v2
	v_add_u32_e32 v2, 1, v2
	s_and_b32 s98, s100, 0xff
	s_add_u32 s98, s98, 2
	s_bfe_u32 s99, s100, 0x80008
	s_mul_i32 s98, s98, s99
	v_mov_b32_e32 v4, 0
	v_mov_b32_e32 v1, 1
	v_cmp_eq_u32_e32 vcc, s98, v2
	s_waitcnt lgkmcnt(0)
	s_and_b32 s98, s100, 0xff
	s_add_u32 s98, s98, 1
	s_bfe_u32 s99, s100, 0x80010
	s_mul_i32 s99, s99, s98
	s_add_u32 s99, s99, s101
	s_add_u32 s100, s100, 1
	s_and_saveexec_b64 s[4:5], vcc
	s_cbranch_execz .Lhs_nl_9
	buffer_wbl2 sc1
	s_waitcnt vmcnt(0)
	global_atomic_add v4, v1, s[2:3] offset:36

; __device__ void tconv(unsigned char* smem, const float* src, int ldsrc, int col0, int N, int K, u16* dst, int ldd) {
;     float* T = (float*)smem;
;     const int tid = threadIdx.x, tilesN = N >> 6, ntile = tilesN * (K >> 6);
;     const int lr = tid >> 4, lc = (tid & 15) * 4;
;     const int sn = tid >> 3, sk = (tid & 7) * 8;
;     int tile = blockIdx.x;
;     f32x4 v0 = {0.f, 0.f, 0.f, 0.f}, v1 = {0.f, 0.f, 0.f, 0.f};
;     if (tile < ntile) { const int tn = tile % tilesN, tk = tile / tilesN; const float* s = src + (size_t)(tk * 64 + lr) * ldsrc + col0 + tn * 64 + lc;
;         v0 = __builtin_nontemporal_load((const f32x4*)s); v1 = __builtin_nontemporal_load((const f32x4*)(s + (size_t)32 * ldsrc)); }
;     for (; tile < ntile; tile += gridDim.x) {
;         const int tn = tile % tilesN, tk = tile / tilesN;
; #pragma unroll
;         for (int j = 0; j < 4; ++j) { T[lr * 65 + lc + j] = v0[j]; T[(lr + 32) * 65 + lc + j] = v1[j]; }
;         asm volatile("s_waitcnt lgkmcnt(0)" ::: "memory"); __builtin_amdgcn_s_barrier(); asm volatile("" ::: "memory");
;         const int nx = tile + gridDim.x;
;         if (nx < ntile) { const int tn2 = nx % tilesN, tk2 = nx / tilesN; const float* s = src + (size_t)(tk2 * 64 + lr) * ldsrc + col0 + tn2 * 64 + lc;
;             v0 = __builtin_nontemporal_load((const f32x4*)s); v1 = __builtin_nontemporal_load((const f32x4*)(s + (size_t)32 * ldsrc)); }
SPLIT9_tconv:
	s_or_b64 exec, exec, s[0:1]
	s_cmpk_gt_i32 s70, 0x7ff
	s_cbranch_scc1 SPLIT9_notc
	s_waitcnt vmcnt(0) lgkmcnt(0)
	s_barrier
	v_readlane_b32 s40, v251, 28
	v_readlane_b32 s41, v251, 29
	v_and_b32_e32 v142, 0x3ff, v0
	v_lshrrev_b32_e32 v153, 4, v142
	v_and_b32_e32 v154, 15, v142
	v_lshlrev_b32_e32 v154, 4, v154
	v_lshlrev_b32_e32 v143, 16, v153
	v_add_u32_e32 v143, v143, v154
	v_mul_u32_u24_e32 v145, 0x104, v153
	v_add_u32_e32 v145, v145, v154
	v_add_u32_e32 v146, 0x2080, v145
	v_add_u32_e32 v147, 0x4100, v145
	v_add_u32_e32 v148, 0x6180, v145
	v_lshrrev_b32_e32 v153, 3, v142
	v_and_b32_e32 v154, 7, v142
	v_mul_u32_u24_e32 v149, 0x820, v154
	v_lshl_add_u32 v149, v153, 2, v149
	v_add_u32_e32 v150, 0x400, v149
	v_add_u32_e32 v151, 0x4100, v149
	v_add_u32_e32 v152, 0x4500, v149
	v_lshlrev_b32_e32 v144, 12, v153
	v_lshl_add_u32 v144, v154, 4, v144
	s_add_u32 s44, s64, 0x1c000000
	s_addc_u32 s45, s65, 0
	s_lshl_b32 s54, s62, 1
	s_mov_b32 s46, s70
	s_waitcnt lgkmcnt(0)
	s_add_u32 s40, s40, 0xc000
	s_addc_u32 s41, s41, 0
	s_add_u32 s42, s40, 0x200000
	s_addc_u32 s43, s41, 0
	s_add_i32 s47, s46, s62
	s_cmpk_lt_i32 s47, 0x800
	s_cselect_b32 s47, s47, s46
	s_and_b32 s52, s46, 0x3f
	s_lshr_b32 s53, s46, 6
	s_lshl_b32 s52, s52, 8
	s_lshl_b32 s53, s53, 22
	s_add_i32 s48, s52, s53
	s_and_b32 s52, s47, 0x3f
	s_lshr_b32 s53, s47, 6
	s_lshl_b32 s52, s52, 8
	s_lshl_b32 s53, s53, 22
	s_add_i32 s49, s52, s53
	v_add_u32_e32 v153, s48, v143
	v_add_u32_e32 v172, s49, v143
	global_load_dwordx4 v[70:73], v153, s[40:41] nt
	global_load_dwordx4 v[74:77], v153, s[42:43] nt
	global_load_dwordx4 v[78:81], v172, s[40:41] nt
	global_load_dwordx4 v[82:85], v172, s[42:43] nt
	s_waitcnt vmcnt(0)

; __device__ __forceinline__ u32x4 pack8(const float* f) { u32x4 w; w.x = pk2(f[0], f[1]); w.y = pk2(f[2], f[3]); w.z = pk2(f[4], f[5]); w.w = pk2(f[6], f[7]); return w; }
; __device__ void tconv(unsigned char* smem, const float* src, int ldsrc, int col0, int N, int K, u16* dst, int ldd) {
;     ...
;     for (; tile < ntile; tile += gridDim.x) {
;         const int tn = tile % tilesN, tk = tile / tilesN;
; #pragma unroll
;         for (int j = 0; j < 4; ++j) { T[lr * 65 + lc + j] = v0[j]; T[(lr + 32) * 65 + lc + j] = v1[j]; }
;         asm volatile("s_waitcnt lgkmcnt(0)" ::: "memory"); __builtin_amdgcn_s_barrier(); asm volatile("" ::: "memory");
;         const int nx = tile + gridDim.x;
;         if (nx < ntile) { const int tn2 = nx % tilesN, tk2 = nx / tilesN; const float* s = src + (size_t)(tk2 * 64 + lr) * ldsrc + col0 + tn2 * 64 + lc;
;             v0 = __builtin_nontemporal_load((const f32x4*)s); v1 = __builtin_nontemporal_load((const f32x4*)(s + (size_t)32 * ldsrc)); }
;         float f[8];
; #pragma unroll
;         for (int j = 0; j < 8; ++j) f[j] = T[(sk + j) * 65 + sn];
;         *(u32x4*)(dst + (size_t)(tn * 64 + sn) * ldd + tk * 64 + sk) = pack8(f);
;         asm volatile("s_waitcnt lgkmcnt(0)" ::: "memory"); __builtin_amdgcn_s_barrier(); asm volatile("" ::: "memory");
;     }
;     __syncthreads();
; __global__ void __launch_bounds__(512, 2) mega(Params p) {
;     ...
;         tconv(smem, p.in[39], 2048, 0, 2048, 4096, (u16*)(ws + OFF_W1OUT), 4096); if ((REP_MASK >> 4) & 1) { tconv(smem, p.in[39], 2048, 0, 2048, 4096, (u16*)(ws + OFF_W1OUT), 4096); }
TCV5_noload:
	ds_read2_b32 v[156:157], v149 offset1:65
	ds_read2_b32 v[158:159], v149 offset0:130 offset1:195
	ds_read2_b32 v[160:161], v150 offset0:4 offset1:69
	ds_read2_b32 v[162:163], v150 offset0:134 offset1:199
	ds_read2_b32 v[164:165], v151 offset1:65
	ds_read2_b32 v[166:167], v151 offset0:130 offset1:195
	ds_read2_b32 v[168:169], v152 offset0:4 offset1:69
	ds_read2_b32 v[170:171], v152 offset0:134 offset1:199
	v_add_u32_e32 v154, s50, v144
	v_add_u32_e32 v155, s51, v144
	s_waitcnt lgkmcnt(7)
	v_cvt_pk_bf16_f32 v156, v156, v157
	s_waitcnt lgkmcnt(6)
	v_cvt_pk_bf16_f32 v157, v158, v159
	s_waitcnt lgkmcnt(5)
	v_cvt_pk_bf16_f32 v158, v160, v161
	s_waitcnt lgkmcnt(4)
	v_cvt_pk_bf16_f32 v159, v162, v163
	global_store_dwordx4 v154, v[156:159], s[44:45]
	s_waitcnt lgkmcnt(3)
	v_cvt_pk_bf16_f32 v164, v164, v165
	s_waitcnt lgkmcnt(2)
	v_cvt_pk_bf16_f32 v165, v166, v167
	s_waitcnt lgkmcnt(1)
	v_cvt_pk_bf16_f32 v166, v168, v169
	s_waitcnt lgkmcnt(0)
	v_cvt_pk_bf16_f32 v167, v170, v171
	global_store_dwordx4 v155, v[164:167], s[44:45]
	s_barrier
	s_cmpk_lt_i32 s46, 0x800
	s_waitcnt vmcnt(2)
	s_cbranch_scc1 TCV5_body
	s_waitcnt vmcnt(0) lgkmcnt(0)
	s_barrier
	v_readlane_b32 s40, v250, 15
	v_readlane_b32 s41, v250, 16
	v_and_b32_e32 v142, 0x3ff, v0
	v_lshrrev_b32_e32 v153, 4, v142
	v_and_b32_e32 v154, 15, v142
	v_lshlrev_b32_e32 v154, 4, v154
	v_lshlrev_b32_e32 v143, 13, v153
	v_add_u32_e32 v143, v143, v154
	v_mul_u32_u24_e32 v145, 0x104, v153
	v_add_u32_e32 v145, v145, v154
	v_add_u32_e32 v146, 0x2080, v145
	v_add_u32_e32 v147, 0x4100, v145
	v_add_u32_e32 v148, 0x6180, v145
	v_lshrrev_b32_e32 v153, 3, v142
	v_and_b32_e32 v154, 7, v142
	v_mul_u32_u24_e32 v149, 0x820, v154
	v_lshl_add_u32 v149, v153, 2, v149
	v_add_u32_e32 v150, 0x400, v149
	v_add_u32_e32 v151, 0x4100, v149
	v_add_u32_e32 v152, 0x4500, v149
	v_lshlrev_b32_e32 v144, 13, v153
	v_lshl_add_u32 v144, v154, 4, v144
	s_add_u32 s44, s64, 0x1d000000
	s_addc_u32 s45, s65, 0
	s_lshl_b32 s54, s62, 1
	s_mov_b32 s46, s70
	s_waitcnt lgkmcnt(0)
	s_add_u32 s42, s40, 0x40000
	s_addc_u32 s43, s41, 0
	s_add_i32 s47, s46, s62
	s_cmpk_lt_i32 s47, 0x800
	s_cselect_b32 s47, s47, s46
	s_and_b32 s52, s46, 0x1f
	s_lshr_b32 s53, s46, 5
	s_lshl_b32 s52, s52, 8
	s_lshl_b32 s53, s53, 19
	s_add_i32 s48, s52, s53
	s_and_b32 s52, s47, 0x1f
	s_lshr_b32 s53, s47, 5
	s_lshl_b32 s52, s52, 8
	s_lshl_b32 s53, s53, 19
	s_add_i32 s49, s52, s53
	v_add_u32_e32 v153, s48, v143
	v_add_u32_e32 v172, s49, v143
	global_load_dwordx4 v[70:73], v153, s[40:41] nt
	global_load_dwordx4 v[74:77], v153, s[42:43] nt
	global_load_dwordx4 v[78:81], v172, s[40:41] nt
	global_load_dwordx4 v[82:85], v172, s[42:43] nt
	s_waitcnt vmcnt(0)

; __global__ void __launch_bounds__(512, 2) mega(Params p) {
;     ...
;     if (IN(9)) {
;     ...
;         ptanh_phase(p);
;         grid.sync();
;         { const unsigned long long tw_ = rwkv2_phase(p, smem); if (PROBE_ROLE >= 0) tp1 += tw_; }
SPLIT9_notc:
	s_waitcnt lgkmcnt(0)
	s_barrier
	v_and_b32_e32 v1, 0x3fffffff, v0
	v_cmp_eq_u32_e32 vcc, 0, v1
	s_and_saveexec_b64 s[0:1], vcc
	s_cbranch_execz .LBB0_842
	v_mov_b32_e32 v4, 0
	s_mov_b64 s[4:5], 0

; __global__ void __launch_bounds__(512, 2) mega(Params p) {
;     ...
;         tconv(smem, p.in[24], 16384, 12288, 4096, 2048, (u16*)(ws + OFF_W1Z), 2048); if ((REP_MASK >> 4) & 1) { tconv(smem, p.in[24], 16384, 12288, 4096, 2048, (u16*)(ws + OFF_W1Z), 2048); }
;         tconv(smem, p.in[39], 2048, 0, 2048, 4096, (u16*)(ws + OFF_W1OUT), 4096); if ((REP_MASK >> 4) & 1) { tconv(smem, p.in[39], 2048, 0, 2048, 4096, (u16*)(ws + OFF_W1OUT), 4096); }
.LBB0_1013:
	s_cmpk_lt_i32 s70, 0x800
	v_lshrrev_b32_e32 v1, 4, v103
	s_cselect_b64 s[0:1], -1, 0
	s_cmpk_gt_i32 s70, 0x7ff
	v_lshrrev_b32_e32 v14, 3, v103
	s_cbranch_scc1 .LBB0_1020
.LBB0_1020:
	s_andn2_b64 vcc, exec, s[0:1]
	s_barrier
	s_cbranch_vccnz .LBB0_1027
.LBB0_1027:
	s_barrier
